# MLA: tile store + global prefetch segment moved from the head to the tail of each barrier-bounded step, so QK MFMAs lead each segment
# baseline (speedup 1.0000x reference)
; #define MLA_LOAD(S, KT) do { const int kc_ = (KT) < nkt ? (KT) : nkt - 1; const bf16_t* Kn_ = Kg + (size_t)kc_ * 64 * 192 + (size_t)tid * 8; const bf16_t* Vn_ = Vg0 + kc_ * 64; \
;         S##k0 = *(const uint4*)(Kn_); S##k1 = *(const uint4*)(Kn_ + 4096); S##k2 = *(const uint4*)(Kn_ + 8192); \
;         S##v0 = *(const uint4*)(Vn_); S##v1 = *(const uint4*)(Vn_ + (size_t)64 * NKEY); } while (0)
; __device__ __forceinline__ void mla_item(const Params& P, int h, int qrow0, int keyrow0, int my_nkt_in, int nkt, char* lds) {
;     ...
;     for (int kt2 = 0; kt2 < nkt; kt2 += 2) {
;         MLA_STORE(x, 1);
;         __builtin_amdgcn_sched_barrier(0);
;         MLA_LOAD(x, kt2 + 3);
;         __builtin_amdgcn_sched_barrier(0);
;         MLA_COMP(kt2, 0);
;         __syncthreads();
;         MLA_STORE(y, 0);
;         __builtin_amdgcn_sched_barrier(0);
;         MLA_LOAD(y, kt2 + 4);
;         __builtin_amdgcn_sched_barrier(0);
;         MLA_COMP(kt2 + 1, 1);
.LBB0_1557:
	v_min_u32_e32 v0, s46, v205
	v_mad_u64_u32 v[4:5], s[50:51], v0, s30, v[208:209]
	v_lshlrev_b32_e32 v0, 6, v0
	ds_write_b128 v216, v[172:175]
	ds_write_b128 v217, v[184:187]
	ds_write_b128 v218, v[192:195]
	v_lshl_add_u64 v[6:7], v[0:1], 1, v[206:207]
	ds_write2_b64 v219, v[176:177], v[178:179] offset1:1
	s_waitcnt vmcnt(5)
	ds_write2_b64 v220, v[196:197], v[198:199] offset1:1
	v_add_co_u32_e32 v8, vcc, 0x2000, v4
	s_nop 1
	v_addc_co_u32_e32 v9, vcc, 0, v5, vcc
	v_add_co_u32_e32 v10, vcc, 0x4000, v4
	s_nop 1
	v_addc_co_u32_e32 v11, vcc, 0, v5, vcc
	global_load_dwordx4 v[184:187], v[8:9], off
	global_load_dwordx4 v[192:195], v[10:11], off
	global_load_dwordx4 v[172:175], v[4:5], off
	global_load_dwordx4 v[176:179], v[6:7], off
	v_add_co_u32_e32 v4, vcc, 0x310000, v6
	s_nop 1
	v_addc_co_u32_e32 v5, vcc, 0, v7, vcc
	global_load_dwordx4 v[196:199], v[4:5], off
	s_add_i32 s47, s47, 1
	s_add_i32 s46, s46, 2
	v_cmp_ge_u32_e32 vcc, s47, v203
	s_or_b64 s[14:15], vcc, s[14:15]
	s_waitcnt lgkmcnt(0)
	s_barrier
	s_andn2_b64 exec, exec, s[14:15]
	s_cbranch_execz .LBB0_1567
.LBB0_1558:
	s_add_i32 s50, s46, -1
	s_add_i32 s47, s46, -4
	s_cmp_ge_i32 s47, s43
	s_cbranch_scc1 .LBB0_1562
	ds_read_b128 v[4:7], v225
	ds_read_b128 v[8:11], v225 offset:12800
	ds_read_b128 v[12:15], v225 offset:32
	ds_read_b128 v[228:231], v225 offset:12832
	ds_read_b128 v[232:235], v225 offset:64
	ds_read_b128 v[236:239], v225 offset:12864
	ds_read_b128 v[240:243], v225 offset:96
	s_waitcnt lgkmcnt(6)
	v_mfma_f32_32x32x16_bf16 v[96:111], v[4:7], v[156:159], 0
	ds_read_b128 v[244:247], v225 offset:12896
	s_waitcnt lgkmcnt(6)
	v_mfma_f32_32x32x16_bf16 v[80:95], v[8:11], v[156:159], 0
	ds_read_b128 v[4:7], v225 offset:128
	s_waitcnt lgkmcnt(6)
	v_mfma_f32_32x32x16_bf16 v[96:111], v[12:15], v[152:155], v[96:111]
	ds_read_b128 v[8:11], v225 offset:12928
	s_waitcnt lgkmcnt(6)
	v_mfma_f32_32x32x16_bf16 v[80:95], v[228:231], v[152:155], v[80:95]
	ds_read_b128 v[12:15], v225 offset:160
	s_waitcnt lgkmcnt(6)
	v_mfma_f32_32x32x16_bf16 v[96:111], v[232:235], v[148:151], v[96:111]
	ds_read_b128 v[228:231], v225 offset:12960
	s_waitcnt lgkmcnt(6)
	v_mfma_f32_32x32x16_bf16 v[80:95], v[236:239], v[148:151], v[80:95]
	ds_read_b128 v[232:235], v225 offset:192
	s_waitcnt lgkmcnt(6)
	v_mfma_f32_32x32x16_bf16 v[96:111], v[240:243], v[144:147], v[96:111]
	ds_read_b128 v[236:239], v225 offset:12992
	s_waitcnt lgkmcnt(6)
	v_mfma_f32_32x32x16_bf16 v[80:95], v[244:247], v[144:147], v[80:95]
	ds_read_b128 v[240:243], v225 offset:224
	s_waitcnt lgkmcnt(6)
	v_mfma_f32_32x32x16_bf16 v[96:111], v[4:7], v[140:143], v[96:111]
	ds_read_b128 v[244:247], v225 offset:13024
	s_waitcnt lgkmcnt(6)
	v_mfma_f32_32x32x16_bf16 v[80:95], v[8:11], v[140:143], v[80:95]
	ds_read_b128 v[4:7], v225 offset:256
	s_waitcnt lgkmcnt(6)
	v_mfma_f32_32x32x16_bf16 v[96:111], v[12:15], v[136:139], v[96:111]
	ds_read_b128 v[8:11], v225 offset:13056
	s_waitcnt lgkmcnt(6)
	v_mfma_f32_32x32x16_bf16 v[80:95], v[228:231], v[136:139], v[80:95]
	ds_read_b128 v[12:15], v225 offset:288
	s_waitcnt lgkmcnt(6)
	v_mfma_f32_32x32x16_bf16 v[96:111], v[232:235], v[132:135], v[96:111]
	ds_read_b128 v[228:231], v225 offset:13088
	s_waitcnt lgkmcnt(6)
	v_mfma_f32_32x32x16_bf16 v[80:95], v[236:239], v[132:135], v[80:95]
	ds_read_b128 v[232:235], v225 offset:320
	s_waitcnt lgkmcnt(6)
	v_mfma_f32_32x32x16_bf16 v[96:111], v[240:243], v[128:131], v[96:111]
	ds_read_b128 v[236:239], v225 offset:13120
	s_waitcnt lgkmcnt(6)
	v_mfma_f32_32x32x16_bf16 v[80:95], v[244:247], v[128:131], v[80:95]
	ds_read_b128 v[240:243], v225 offset:352
	s_waitcnt lgkmcnt(6)
	v_mfma_f32_32x32x16_bf16 v[96:111], v[4:7], v[124:127], v[96:111]
	ds_read_b128 v[244:247], v225 offset:13152
	s_waitcnt lgkmcnt(6)
	v_mfma_f32_32x32x16_bf16 v[80:95], v[8:11], v[124:127], v[80:95]
	s_waitcnt lgkmcnt(5)
	v_mfma_f32_32x32x16_bf16 v[96:111], v[12:15], v[120:123], v[96:111]
	s_waitcnt lgkmcnt(4)
	v_mfma_f32_32x32x16_bf16 v[80:95], v[228:231], v[120:123], v[80:95]
	s_waitcnt lgkmcnt(3)
	v_mfma_f32_32x32x16_bf16 v[96:111], v[232:235], v[116:119], v[96:111]
	s_waitcnt lgkmcnt(2)
	v_mfma_f32_32x32x16_bf16 v[80:95], v[236:239], v[116:119], v[80:95]
	s_waitcnt lgkmcnt(1)
	v_mfma_f32_32x32x16_bf16 v[96:111], v[240:243], v[112:115], v[96:111]
	s_waitcnt lgkmcnt(0)
	v_mfma_f32_32x32x16_bf16 v[80:95], v[244:247], v[112:115], v[80:95]
	v_and_b32_e32 v248, 64, v210
	v_xor_b32_e32 v249, 32, v210
	v_add_u32_e32 v248, 64, v248
	v_cmp_lt_i32_e32 vcc, v249, v248
	ds_read_b64 v[228:229], v223 offset:25600
	ds_read_b64 v[230:231], v223 offset:25616
	ds_read_b64 v[232:233], v223 offset:29952
	ds_read_b64 v[234:235], v223 offset:29968
	ds_read_b64 v[236:237], v223 offset:34304
	ds_read_b64 v[238:239], v223 offset:34320
	ds_read_b64 v[240:241], v223 offset:38656
	ds_read_b64 v[242:243], v223 offset:38672
	ds_read_b64 v[244:245], v223 offset:25632
	ds_read_b64 v[246:247], v223 offset:25648
	v_cndmask_b32_e32 v249, v210, v249, vcc
	v_lshlrev_b32_e32 v249, 2, v249
	s_nop 1
	v_max_f32_e32 v0, v96, v80
	v_max3_f32 v0, v0, v97, v81
	v_max3_f32 v0, v0, v98, v82
	v_max3_f32 v0, v0, v99, v83
	v_max3_f32 v0, v0, v100, v84
	v_max3_f32 v0, v0, v101, v85
	v_max3_f32 v0, v0, v102, v86
	v_max3_f32 v0, v0, v103, v87
	v_max3_f32 v0, v0, v104, v88
	v_max3_f32 v0, v0, v105, v89
	v_max3_f32 v0, v0, v106, v90
	v_max3_f32 v0, v0, v107, v91
	v_max3_f32 v0, v0, v108, v92
	v_max3_f32 v0, v0, v109, v93
	v_max3_f32 v0, v0, v110, v94
	v_max3_f32 v0, v0, v111, v95
	ds_bpermute_b32 v248, v249, v0
	s_waitcnt lgkmcnt(0)
	v_max_f32_e32 v0, v0, v248
	v_max_f32_e32 v248, v226, v226
	v_max_f32_e32 v0, v0, v0
	v_sub_f32_e32 v249, v0, v248
	v_cmp_lt_f32_e32 vcc, 0x41000000, v249
	s_cbranch_vccz .Lmla_keep_a
	v_max_f32_e32 v2, v248, v0
	v_sub_f32_e32 v0, v226, v2
	v_exp_f32_e32 v0, v0
	s_nop 0
	v_pk_mul_f32 v[78:79], v[78:79], v[0:1] op_sel_hi:[1,0]
	v_pk_mul_f32 v[76:77], v[76:77], v[0:1] op_sel_hi:[1,0]
	v_pk_mul_f32 v[74:75], v[74:75], v[0:1] op_sel_hi:[1,0]
	v_pk_mul_f32 v[72:73], v[72:73], v[0:1] op_sel_hi:[1,0]
	v_pk_mul_f32 v[70:71], v[70:71], v[0:1] op_sel_hi:[1,0]
	v_pk_mul_f32 v[68:69], v[68:69], v[0:1] op_sel_hi:[1,0]
	v_pk_mul_f32 v[66:67], v[66:67], v[0:1] op_sel_hi:[1,0]
	v_pk_mul_f32 v[64:65], v[64:65], v[0:1] op_sel_hi:[1,0]
	v_pk_mul_f32 v[62:63], v[62:63], v[0:1] op_sel_hi:[1,0]
	v_pk_mul_f32 v[60:61], v[60:61], v[0:1] op_sel_hi:[1,0]
	v_pk_mul_f32 v[58:59], v[58:59], v[0:1] op_sel_hi:[1,0]
	v_pk_mul_f32 v[56:57], v[56:57], v[0:1] op_sel_hi:[1,0]
	v_pk_mul_f32 v[54:55], v[54:55], v[0:1] op_sel_hi:[1,0]
	v_pk_mul_f32 v[52:53], v[52:53], v[0:1] op_sel_hi:[1,0]
	v_pk_mul_f32 v[50:51], v[50:51], v[0:1] op_sel_hi:[1,0]
	v_pk_mul_f32 v[48:49], v[48:49], v[0:1] op_sel_hi:[1,0]
	v_pk_mul_f32 v[46:47], v[46:47], v[0:1] op_sel_hi:[1,0]
	v_pk_mul_f32 v[44:45], v[44:45], v[0:1] op_sel_hi:[1,0]
	v_pk_mul_f32 v[42:43], v[42:43], v[0:1] op_sel_hi:[1,0]
	v_pk_mul_f32 v[40:41], v[40:41], v[0:1] op_sel_hi:[1,0]
	v_pk_mul_f32 v[38:39], v[38:39], v[0:1] op_sel_hi:[1,0]
	v_pk_mul_f32 v[36:37], v[36:37], v[0:1] op_sel_hi:[1,0]
	v_pk_mul_f32 v[34:35], v[34:35], v[0:1] op_sel_hi:[1,0]
	v_pk_mul_f32 v[32:33], v[32:33], v[0:1] op_sel_hi:[1,0]
	v_pk_mul_f32 v[30:31], v[30:31], v[0:1] op_sel_hi:[1,0]
	v_pk_mul_f32 v[28:29], v[28:29], v[0:1] op_sel_hi:[1,0]
	v_pk_mul_f32 v[26:27], v[26:27], v[0:1] op_sel_hi:[1,0]
	v_pk_mul_f32 v[24:25], v[24:25], v[0:1] op_sel_hi:[1,0]
	v_pk_mul_f32 v[22:23], v[22:23], v[0:1] op_sel_hi:[1,0]
	v_pk_mul_f32 v[20:21], v[20:21], v[0:1] op_sel_hi:[1,0]
	v_pk_mul_f32 v[18:19], v[18:19], v[0:1] op_sel_hi:[1,0]
	v_pk_mul_f32 v[16:17], v[16:17], v[0:1] op_sel_hi:[1,0]
	s_branch .Lmla_join_a
	.Lmla_keep_a:
	v_mov_b32_e32 v2, v248
	v_mov_b32_e32 v0, 1.0
	.Lmla_join_a:
	v_sub_f32_e32 v248, v96, v2
	v_exp_f32_e32 v96, v248
	v_sub_f32_e32 v249, v97, v2
	v_exp_f32_e32 v97, v249
	v_sub_f32_e32 v248, v98, v2
	v_exp_f32_e32 v98, v248
	v_sub_f32_e32 v249, v99, v2
	v_exp_f32_e32 v99, v249
	v_sub_f32_e32 v248, v100, v2
	v_exp_f32_e32 v100, v248
	v_sub_f32_e32 v249, v101, v2
	v_exp_f32_e32 v101, v249
	v_sub_f32_e32 v248, v102, v2
	v_exp_f32_e32 v102, v248
	v_sub_f32_e32 v249, v103, v2
	v_exp_f32_e32 v103, v249
	s_nop 0
	v_cvt_pk_bf16_f32 v8, v96, v97
	v_cvt_pk_bf16_f32 v9, v98, v99
	v_cvt_pk_bf16_f32 v10, v100, v101
	v_cvt_pk_bf16_f32 v11, v102, v103
	v_sub_f32_e32 v248, v104, v2
	v_exp_f32_e32 v104, v248
	v_mfma_f32_32x32x16_bf16 v[64:79], v[228:231], v[8:11], v[64:79]
	ds_read_b64 v[228:229], v223 offset:29984
	ds_read_b64 v[230:231], v223 offset:30000
	v_sub_f32_e32 v249, v105, v2
	v_exp_f32_e32 v105, v249
	v_mfma_f32_32x32x16_bf16 v[48:63], v[232:235], v[8:11], v[48:63]
	ds_read_b64 v[232:233], v223 offset:34336
	ds_read_b64 v[234:235], v223 offset:34352
	v_sub_f32_e32 v248, v106, v2
	v_exp_f32_e32 v106, v248
	v_sub_f32_e32 v249, v107, v2
	v_exp_f32_e32 v107, v249
	v_mfma_f32_32x32x16_bf16 v[32:47], v[236:239], v[8:11], v[32:47]
	ds_read_b64 v[236:237], v223 offset:38688
	ds_read_b64 v[238:239], v223 offset:38704
	v_sub_f32_e32 v248, v108, v2
	v_exp_f32_e32 v108, v248
	v_sub_f32_e32 v249, v109, v2
	v_exp_f32_e32 v109, v249
	v_mfma_f32_32x32x16_bf16 v[16:31], v[240:243], v[8:11], v[16:31]
	ds_read_b64 v[240:241], v223 offset:25664
	ds_read_b64 v[242:243], v223 offset:25680
	v_sub_f32_e32 v248, v110, v2
	v_exp_f32_e32 v110, v248
	v_sub_f32_e32 v249, v111, v2
	v_exp_f32_e32 v111, v249
	s_nop 0
	v_cvt_pk_bf16_f32 v4, v104, v105
	v_cvt_pk_bf16_f32 v5, v106, v107
	v_cvt_pk_bf16_f32 v6, v108, v109
	v_cvt_pk_bf16_f32 v7, v110, v111
	s_nop 1
	v_mfma_f32_32x32x16_bf16 v[64:79], v[244:247], v[4:7], v[64:79]
	ds_read_b64 v[244:245], v223 offset:30016
	ds_read_b64 v[246:247], v223 offset:30032
	v_sub_f32_e32 v248, v80, v2
	v_exp_f32_e32 v80, v248
	v_sub_f32_e32 v249, v81, v2
	v_exp_f32_e32 v81, v249
	s_waitcnt lgkmcnt(8)
	v_mfma_f32_32x32x16_bf16 v[48:63], v[228:231], v[4:7], v[48:63]
	ds_read_b64 v[228:229], v223 offset:34368
	ds_read_b64 v[230:231], v223 offset:34384
	v_sub_f32_e32 v248, v82, v2
	v_exp_f32_e32 v82, v248
	v_sub_f32_e32 v249, v83, v2
	v_exp_f32_e32 v83, v249
	s_waitcnt lgkmcnt(8)
	v_mfma_f32_32x32x16_bf16 v[32:47], v[232:235], v[4:7], v[32:47]
	ds_read_b64 v[232:233], v223 offset:38720
	ds_read_b64 v[234:235], v223 offset:38736
	v_sub_f32_e32 v248, v84, v2
	v_exp_f32_e32 v84, v248
	v_sub_f32_e32 v249, v85, v2
	v_exp_f32_e32 v85, v249
	s_waitcnt lgkmcnt(8)
	v_mfma_f32_32x32x16_bf16 v[16:31], v[236:239], v[4:7], v[16:31]
	ds_read_b64 v[236:237], v223 offset:25696
	ds_read_b64 v[238:239], v223 offset:25712
	v_sub_f32_e32 v248, v86, v2
	v_exp_f32_e32 v86, v248
	v_sub_f32_e32 v249, v87, v2
	v_exp_f32_e32 v87, v249
	s_nop 0
	v_cvt_pk_bf16_f32 v12, v80, v81
	v_cvt_pk_bf16_f32 v13, v82, v83
	v_cvt_pk_bf16_f32 v14, v84, v85
	v_cvt_pk_bf16_f32 v15, v86, v87
	s_nop 1
	s_waitcnt lgkmcnt(8)
	v_mfma_f32_32x32x16_bf16 v[64:79], v[240:243], v[12:15], v[64:79]
	ds_read_b64 v[240:241], v223 offset:30048
	ds_read_b64 v[242:243], v223 offset:30064
	v_sub_f32_e32 v248, v88, v2
	v_exp_f32_e32 v88, v248
	v_sub_f32_e32 v249, v89, v2
	v_exp_f32_e32 v89, v249
	s_waitcnt lgkmcnt(8)
	v_mfma_f32_32x32x16_bf16 v[48:63], v[244:247], v[12:15], v[48:63]
	ds_read_b64 v[244:245], v223 offset:34400
	ds_read_b64 v[246:247], v223 offset:34416
	v_sub_f32_e32 v248, v90, v2
	v_exp_f32_e32 v90, v248
	v_sub_f32_e32 v249, v91, v2
	v_exp_f32_e32 v91, v249
	s_waitcnt lgkmcnt(8)
	v_mfma_f32_32x32x16_bf16 v[32:47], v[228:231], v[12:15], v[32:47]
	ds_read_b64 v[228:229], v223 offset:38752
	ds_read_b64 v[230:231], v223 offset:38768
	v_sub_f32_e32 v248, v92, v2
	v_exp_f32_e32 v92, v248
	v_sub_f32_e32 v249, v93, v2
	v_exp_f32_e32 v93, v249
	s_waitcnt lgkmcnt(8)
	v_mfma_f32_32x32x16_bf16 v[16:31], v[232:235], v[12:15], v[16:31]
	v_sub_f32_e32 v248, v94, v2
	v_exp_f32_e32 v94, v248
	v_sub_f32_e32 v249, v95, v2
	v_exp_f32_e32 v95, v249
	s_nop 0
	v_cvt_pk_bf16_f32 v8, v88, v89
	v_cvt_pk_bf16_f32 v9, v90, v91
	v_cvt_pk_bf16_f32 v10, v92, v93
	v_cvt_pk_bf16_f32 v11, v94, v95
	s_nop 1
	s_waitcnt lgkmcnt(6)
	v_mfma_f32_32x32x16_bf16 v[64:79], v[236:239], v[8:11], v[64:79]
	v_add_f32_e32 v3, v80, v96
	v_add_f32_e32 v248, v81, v97
	v_add_f32_e32 v3, v248, v3
	v_add_f32_e32 v249, v82, v98
	v_add_f32_e32 v3, v249, v3
	v_add_f32_e32 v248, v83, v99
	v_add_f32_e32 v3, v248, v3
	v_add_f32_e32 v249, v84, v100
	s_waitcnt lgkmcnt(4)
	v_mfma_f32_32x32x16_bf16 v[48:63], v[240:243], v[8:11], v[48:63]
	v_add_f32_e32 v3, v249, v3
	v_add_f32_e32 v248, v85, v101
	v_add_f32_e32 v3, v248, v3
	v_add_f32_e32 v249, v86, v102
	v_add_f32_e32 v3, v249, v3
	v_add_f32_e32 v248, v87, v103
	v_add_f32_e32 v3, v248, v3
	v_add_f32_e32 v249, v88, v104
	s_waitcnt lgkmcnt(2)
	v_mfma_f32_32x32x16_bf16 v[32:47], v[244:247], v[8:11], v[32:47]
	v_add_f32_e32 v3, v249, v3
	v_add_f32_e32 v248, v89, v105
	v_add_f32_e32 v3, v248, v3
	v_add_f32_e32 v249, v90, v106
	v_add_f32_e32 v3, v249, v3
	v_add_f32_e32 v248, v91, v107
	v_add_f32_e32 v3, v248, v3
	v_add_f32_e32 v249, v92, v108
	s_waitcnt lgkmcnt(0)
	v_mfma_f32_32x32x16_bf16 v[16:31], v[228:231], v[8:11], v[16:31]
	v_add_f32_e32 v3, v249, v3
	v_add_f32_e32 v248, v93, v109
	v_add_f32_e32 v3, v248, v3
	v_add_f32_e32 v249, v94, v110
	v_add_f32_e32 v3, v249, v3
	v_add_f32_e32 v248, v95, v111
	v_add_f32_e32 v3, v248, v3
	v_fmac_f32_e32 v3, v221, v0
	v_mov_b32_e32 v221, v3
	s_branch .LBB0_1563

; #define MLA_LOAD(S, KT) do { const int kc_ = (KT) < nkt ? (KT) : nkt - 1; const bf16_t* Kn_ = Kg + (size_t)kc_ * 64 * 192 + (size_t)tid * 8; const bf16_t* Vn_ = Vg0 + kc_ * 64; \
;         S##k0 = *(const uint4*)(Kn_); S##k1 = *(const uint4*)(Kn_ + 4096); S##k2 = *(const uint4*)(Kn_ + 8192); \
;         S##v0 = *(const uint4*)(Vn_); S##v1 = *(const uint4*)(Vn_ + (size_t)64 * NKEY); } while (0)
; __device__ __forceinline__ void mla_item(const Params& P, int h, int qrow0, int keyrow0, int my_nkt_in, int nkt, char* lds) {
;     ...
;     for (int kt2 = 0; kt2 < nkt; kt2 += 2) {
;         MLA_STORE(x, 1);
;         __builtin_amdgcn_sched_barrier(0);
;         MLA_LOAD(x, kt2 + 3);
;         __builtin_amdgcn_sched_barrier(0);
;         MLA_COMP(kt2, 0);
;         __syncthreads();
;         MLA_STORE(y, 0);
;         __builtin_amdgcn_sched_barrier(0);
;         MLA_LOAD(y, kt2 + 4);
;         __builtin_amdgcn_sched_barrier(0);
;         MLA_COMP(kt2 + 1, 1);
.LBB0_1563:
	v_min_u32_e32 v0, s50, v205
	v_mad_u64_u32 v[250:251], s[50:51], v0, s30, v[208:209]
	v_lshlrev_b32_e32 v0, 6, v0
	v_lshl_add_u64 v[4:5], v[0:1], 1, v[206:207]
	v_add_u32_e32 v0, 0xa800, v222
	s_waitcnt vmcnt(7)
	ds_write_b128 v216, v[164:167] offset:43008
	s_waitcnt vmcnt(8)
	ds_write_b128 v217, v[160:163] offset:43008
	s_waitcnt vmcnt(7)
	ds_write_b128 v218, v[168:171] offset:43008
	s_waitcnt vmcnt(3)
	ds_write2_b64 v0, v[180:181], v[182:183] offset1:1
	v_add_u32_e32 v0, 0xca00, v222
	s_waitcnt vmcnt(1)
	ds_write2_b64 v0, v[188:189], v[190:191] offset1:1
	v_add_co_u32_e32 v6, vcc, 0x2000, v250
	s_nop 1
	v_addc_co_u32_e32 v7, vcc, 0, v251, vcc
	v_add_co_u32_e32 v8, vcc, 0x4000, v250
	s_nop 1
	v_addc_co_u32_e32 v9, vcc, 0, v251, vcc
	global_load_dwordx4 v[160:163], v[6:7], off
	global_load_dwordx4 v[168:171], v[8:9], off
	global_load_dwordx4 v[164:167], v[250:251], off
	global_load_dwordx4 v[180:183], v[4:5], off
	v_add_co_u32_e32 v250, vcc, 0x310000, v4
	s_nop 1
	v_addc_co_u32_e32 v251, vcc, 0, v5, vcc
	global_load_dwordx4 v[188:191], v[250:251], off
	s_waitcnt lgkmcnt(0)
	s_barrier
	s_add_i32 s47, s47, 1
	s_cmp_ge_i32 s47, s43
	s_cbranch_scc1 .LBB0_1556
	ds_read_b128 v[4:7], v225 offset:43008
	ds_read_b128 v[8:11], v225 offset:55808
	ds_read_b128 v[12:15], v225 offset:43040
	ds_read_b128 v[228:231], v225 offset:55840
	ds_read_b128 v[232:235], v225 offset:43072
	ds_read_b128 v[236:239], v225 offset:55872
	ds_read_b128 v[240:243], v225 offset:43104
	s_waitcnt lgkmcnt(6)
	v_mfma_f32_32x32x16_bf16 v[96:111], v[4:7], v[156:159], 0
	ds_read_b128 v[244:247], v225 offset:55904
	s_waitcnt lgkmcnt(6)
	v_mfma_f32_32x32x16_bf16 v[80:95], v[8:11], v[156:159], 0
	ds_read_b128 v[4:7], v225 offset:43136
	s_waitcnt lgkmcnt(6)
	v_mfma_f32_32x32x16_bf16 v[96:111], v[12:15], v[152:155], v[96:111]
	ds_read_b128 v[8:11], v225 offset:55936
	s_waitcnt lgkmcnt(6)
	v_mfma_f32_32x32x16_bf16 v[80:95], v[228:231], v[152:155], v[80:95]
	ds_read_b128 v[12:15], v225 offset:43168
	s_waitcnt lgkmcnt(6)
	v_mfma_f32_32x32x16_bf16 v[96:111], v[232:235], v[148:151], v[96:111]
	ds_read_b128 v[228:231], v225 offset:55968
	s_waitcnt lgkmcnt(6)
	v_mfma_f32_32x32x16_bf16 v[80:95], v[236:239], v[148:151], v[80:95]
	ds_read_b128 v[232:235], v225 offset:43200
	s_waitcnt lgkmcnt(6)
	v_mfma_f32_32x32x16_bf16 v[96:111], v[240:243], v[144:147], v[96:111]
	ds_read_b128 v[236:239], v225 offset:56000
	s_waitcnt lgkmcnt(6)
	v_mfma_f32_32x32x16_bf16 v[80:95], v[244:247], v[144:147], v[80:95]
	ds_read_b128 v[240:243], v225 offset:43232
	s_waitcnt lgkmcnt(6)
	v_mfma_f32_32x32x16_bf16 v[96:111], v[4:7], v[140:143], v[96:111]
	ds_read_b128 v[244:247], v225 offset:56032
	s_waitcnt lgkmcnt(6)
	v_mfma_f32_32x32x16_bf16 v[80:95], v[8:11], v[140:143], v[80:95]
	ds_read_b128 v[4:7], v225 offset:43264
	s_waitcnt lgkmcnt(6)
	v_mfma_f32_32x32x16_bf16 v[96:111], v[12:15], v[136:139], v[96:111]
	ds_read_b128 v[8:11], v225 offset:56064
	s_waitcnt lgkmcnt(6)
	v_mfma_f32_32x32x16_bf16 v[80:95], v[228:231], v[136:139], v[80:95]
	ds_read_b128 v[12:15], v225 offset:43296
	s_waitcnt lgkmcnt(6)
	v_mfma_f32_32x32x16_bf16 v[96:111], v[232:235], v[132:135], v[96:111]
	ds_read_b128 v[228:231], v225 offset:56096
	s_waitcnt lgkmcnt(6)
	v_mfma_f32_32x32x16_bf16 v[80:95], v[236:239], v[132:135], v[80:95]
	ds_read_b128 v[232:235], v225 offset:43328
	s_waitcnt lgkmcnt(6)
	v_mfma_f32_32x32x16_bf16 v[96:111], v[240:243], v[128:131], v[96:111]
	ds_read_b128 v[236:239], v225 offset:56128
	s_waitcnt lgkmcnt(6)
	v_mfma_f32_32x32x16_bf16 v[80:95], v[244:247], v[128:131], v[80:95]
	ds_read_b128 v[240:243], v225 offset:43360
	s_waitcnt lgkmcnt(6)
	v_mfma_f32_32x32x16_bf16 v[96:111], v[4:7], v[124:127], v[96:111]
	ds_read_b128 v[244:247], v225 offset:56160
	s_waitcnt lgkmcnt(6)
	v_mfma_f32_32x32x16_bf16 v[80:95], v[8:11], v[124:127], v[80:95]
	s_waitcnt lgkmcnt(5)
	v_mfma_f32_32x32x16_bf16 v[96:111], v[12:15], v[120:123], v[96:111]
	s_waitcnt lgkmcnt(4)
	v_mfma_f32_32x32x16_bf16 v[80:95], v[228:231], v[120:123], v[80:95]
	s_waitcnt lgkmcnt(3)
	v_mfma_f32_32x32x16_bf16 v[96:111], v[232:235], v[116:119], v[96:111]
	s_waitcnt lgkmcnt(2)
	v_mfma_f32_32x32x16_bf16 v[80:95], v[236:239], v[116:119], v[80:95]
	s_waitcnt lgkmcnt(1)
	v_mfma_f32_32x32x16_bf16 v[96:111], v[240:243], v[112:115], v[96:111]
	s_waitcnt lgkmcnt(0)
	v_mfma_f32_32x32x16_bf16 v[80:95], v[244:247], v[112:115], v[80:95]
	v_and_b32_e32 v248, 64, v210
	v_xor_b32_e32 v249, 32, v210
	v_add_u32_e32 v248, 64, v248
	v_cmp_lt_i32_e32 vcc, v249, v248
	ds_read_b64 v[228:229], v224 offset:0
	ds_read_b64 v[230:231], v224 offset:16
	ds_read_b64 v[232:233], v224 offset:4352
	ds_read_b64 v[234:235], v224 offset:4368
	ds_read_b64 v[236:237], v224 offset:8704
	ds_read_b64 v[238:239], v224 offset:8720
	ds_read_b64 v[240:241], v224 offset:13056
	ds_read_b64 v[242:243], v224 offset:13072
	ds_read_b64 v[244:245], v224 offset:32
	ds_read_b64 v[246:247], v224 offset:48
	v_cndmask_b32_e32 v249, v210, v249, vcc
	v_lshlrev_b32_e32 v249, 2, v249
	s_nop 1
	v_max_f32_e32 v0, v96, v80
	v_max3_f32 v0, v0, v97, v81
	v_max3_f32 v0, v0, v98, v82
	v_max3_f32 v0, v0, v99, v83
	v_max3_f32 v0, v0, v100, v84
	v_max3_f32 v0, v0, v101, v85
	v_max3_f32 v0, v0, v102, v86
	v_max3_f32 v0, v0, v103, v87
	v_max3_f32 v0, v0, v104, v88
	v_max3_f32 v0, v0, v105, v89
	v_max3_f32 v0, v0, v106, v90
	v_max3_f32 v0, v0, v107, v91
	v_max3_f32 v0, v0, v108, v92
	v_max3_f32 v0, v0, v109, v93
	v_max3_f32 v0, v0, v110, v94
	v_max3_f32 v0, v0, v111, v95
	ds_bpermute_b32 v248, v249, v0
	s_waitcnt lgkmcnt(0)
	v_max_f32_e32 v0, v0, v248
	v_max_f32_e32 v248, v2, v2
	v_max_f32_e32 v0, v0, v0
	v_sub_f32_e32 v249, v0, v248
	v_cmp_lt_f32_e32 vcc, 0x41000000, v249
	s_cbranch_vccz .Lmla_keep_b
	v_max_f32_e32 v226, v248, v0
	v_sub_f32_e32 v0, v2, v226
	v_exp_f32_e32 v0, v0
	s_nop 0
	v_pk_mul_f32 v[78:79], v[78:79], v[0:1] op_sel_hi:[1,0]
	v_pk_mul_f32 v[76:77], v[76:77], v[0:1] op_sel_hi:[1,0]
	v_pk_mul_f32 v[74:75], v[74:75], v[0:1] op_sel_hi:[1,0]
	v_pk_mul_f32 v[72:73], v[72:73], v[0:1] op_sel_hi:[1,0]
	v_pk_mul_f32 v[70:71], v[70:71], v[0:1] op_sel_hi:[1,0]
	v_pk_mul_f32 v[68:69], v[68:69], v[0:1] op_sel_hi:[1,0]
	v_pk_mul_f32 v[66:67], v[66:67], v[0:1] op_sel_hi:[1,0]
	v_pk_mul_f32 v[64:65], v[64:65], v[0:1] op_sel_hi:[1,0]
	v_pk_mul_f32 v[62:63], v[62:63], v[0:1] op_sel_hi:[1,0]
	v_pk_mul_f32 v[60:61], v[60:61], v[0:1] op_sel_hi:[1,0]
	v_pk_mul_f32 v[58:59], v[58:59], v[0:1] op_sel_hi:[1,0]
	v_pk_mul_f32 v[56:57], v[56:57], v[0:1] op_sel_hi:[1,0]
	v_pk_mul_f32 v[54:55], v[54:55], v[0:1] op_sel_hi:[1,0]
	v_pk_mul_f32 v[52:53], v[52:53], v[0:1] op_sel_hi:[1,0]
	v_pk_mul_f32 v[50:51], v[50:51], v[0:1] op_sel_hi:[1,0]
	v_pk_mul_f32 v[48:49], v[48:49], v[0:1] op_sel_hi:[1,0]
	v_pk_mul_f32 v[46:47], v[46:47], v[0:1] op_sel_hi:[1,0]
	v_pk_mul_f32 v[44:45], v[44:45], v[0:1] op_sel_hi:[1,0]
	v_pk_mul_f32 v[42:43], v[42:43], v[0:1] op_sel_hi:[1,0]
	v_pk_mul_f32 v[40:41], v[40:41], v[0:1] op_sel_hi:[1,0]
	v_pk_mul_f32 v[38:39], v[38:39], v[0:1] op_sel_hi:[1,0]
	v_pk_mul_f32 v[36:37], v[36:37], v[0:1] op_sel_hi:[1,0]
	v_pk_mul_f32 v[34:35], v[34:35], v[0:1] op_sel_hi:[1,0]
	v_pk_mul_f32 v[32:33], v[32:33], v[0:1] op_sel_hi:[1,0]
	v_pk_mul_f32 v[30:31], v[30:31], v[0:1] op_sel_hi:[1,0]
	v_pk_mul_f32 v[28:29], v[28:29], v[0:1] op_sel_hi:[1,0]
	v_pk_mul_f32 v[26:27], v[26:27], v[0:1] op_sel_hi:[1,0]
	v_pk_mul_f32 v[24:25], v[24:25], v[0:1] op_sel_hi:[1,0]
	v_pk_mul_f32 v[22:23], v[22:23], v[0:1] op_sel_hi:[1,0]
	v_pk_mul_f32 v[20:21], v[20:21], v[0:1] op_sel_hi:[1,0]
	v_pk_mul_f32 v[18:19], v[18:19], v[0:1] op_sel_hi:[1,0]
	v_pk_mul_f32 v[16:17], v[16:17], v[0:1] op_sel_hi:[1,0]
	s_branch .Lmla_join_b
; __device__ __forceinline__ void mla_item(const Params& P, int h, int qrow0, int keyrow0, int my_nkt_in, int nkt, char* lds) {
;     ...
;         __syncthreads();
	.Lmla_keep_b:
	v_mov_b32_e32 v226, v248
	v_mov_b32_e32 v0, 1.0
	.Lmla_join_b:
	v_sub_f32_e32 v248, v96, v226
	v_exp_f32_e32 v96, v248
	v_sub_f32_e32 v249, v97, v226
	v_exp_f32_e32 v97, v249
	v_sub_f32_e32 v248, v98, v226
	v_exp_f32_e32 v98, v248
	v_sub_f32_e32 v249, v99, v226
	v_exp_f32_e32 v99, v249
	v_sub_f32_e32 v248, v100, v226
	v_exp_f32_e32 v100, v248
	v_sub_f32_e32 v249, v101, v226
	v_exp_f32_e32 v101, v249
	v_sub_f32_e32 v248, v102, v226
	v_exp_f32_e32 v102, v248
	v_sub_f32_e32 v249, v103, v226
	v_exp_f32_e32 v103, v249
	s_nop 0
	v_cvt_pk_bf16_f32 v8, v96, v97
	v_cvt_pk_bf16_f32 v9, v98, v99
	v_cvt_pk_bf16_f32 v10, v100, v101
	v_cvt_pk_bf16_f32 v11, v102, v103
	v_sub_f32_e32 v248, v104, v226
	v_exp_f32_e32 v104, v248
	v_mfma_f32_32x32x16_bf16 v[64:79], v[228:231], v[8:11], v[64:79]
	ds_read_b64 v[228:229], v224 offset:4384
	ds_read_b64 v[230:231], v224 offset:4400
	v_sub_f32_e32 v249, v105, v226
	v_exp_f32_e32 v105, v249
	v_mfma_f32_32x32x16_bf16 v[48:63], v[232:235], v[8:11], v[48:63]
	ds_read_b64 v[232:233], v224 offset:8736
	ds_read_b64 v[234:235], v224 offset:8752
	v_sub_f32_e32 v248, v106, v226
	v_exp_f32_e32 v106, v248
	v_sub_f32_e32 v249, v107, v226
	v_exp_f32_e32 v107, v249
	v_mfma_f32_32x32x16_bf16 v[32:47], v[236:239], v[8:11], v[32:47]
	ds_read_b64 v[236:237], v224 offset:13088
	ds_read_b64 v[238:239], v224 offset:13104
	v_sub_f32_e32 v248, v108, v226
	v_exp_f32_e32 v108, v248
	v_sub_f32_e32 v249, v109, v226
	v_exp_f32_e32 v109, v249
	v_mfma_f32_32x32x16_bf16 v[16:31], v[240:243], v[8:11], v[16:31]
	ds_read_b64 v[240:241], v224 offset:64
	ds_read_b64 v[242:243], v224 offset:80
	v_sub_f32_e32 v248, v110, v226
	v_exp_f32_e32 v110, v248
	v_sub_f32_e32 v249, v111, v226
	v_exp_f32_e32 v111, v249
	s_nop 0
	v_cvt_pk_bf16_f32 v4, v104, v105
	v_cvt_pk_bf16_f32 v5, v106, v107
	v_cvt_pk_bf16_f32 v6, v108, v109
	v_cvt_pk_bf16_f32 v7, v110, v111
	s_nop 1
	v_mfma_f32_32x32x16_bf16 v[64:79], v[244:247], v[4:7], v[64:79]
	ds_read_b64 v[244:245], v224 offset:4416
	ds_read_b64 v[246:247], v224 offset:4432
	v_sub_f32_e32 v248, v80, v226
	v_exp_f32_e32 v80, v248
	v_sub_f32_e32 v249, v81, v226
	v_exp_f32_e32 v81, v249
	s_waitcnt lgkmcnt(8)
	v_mfma_f32_32x32x16_bf16 v[48:63], v[228:231], v[4:7], v[48:63]
	ds_read_b64 v[228:229], v224 offset:8768
	ds_read_b64 v[230:231], v224 offset:8784
	v_sub_f32_e32 v248, v82, v226
	v_exp_f32_e32 v82, v248
	v_sub_f32_e32 v249, v83, v226
	v_exp_f32_e32 v83, v249
	s_waitcnt lgkmcnt(8)
	v_mfma_f32_32x32x16_bf16 v[32:47], v[232:235], v[4:7], v[32:47]
	ds_read_b64 v[232:233], v224 offset:13120
	ds_read_b64 v[234:235], v224 offset:13136
	v_sub_f32_e32 v248, v84, v226
	v_exp_f32_e32 v84, v248
	v_sub_f32_e32 v249, v85, v226
	v_exp_f32_e32 v85, v249
	s_waitcnt lgkmcnt(8)
	v_mfma_f32_32x32x16_bf16 v[16:31], v[236:239], v[4:7], v[16:31]
	ds_read_b64 v[236:237], v224 offset:96
	ds_read_b64 v[238:239], v224 offset:112
	v_sub_f32_e32 v248, v86, v226
	v_exp_f32_e32 v86, v248
	v_sub_f32_e32 v249, v87, v226
	v_exp_f32_e32 v87, v249
	s_nop 0
	v_cvt_pk_bf16_f32 v12, v80, v81
	v_cvt_pk_bf16_f32 v13, v82, v83
	v_cvt_pk_bf16_f32 v14, v84, v85
	v_cvt_pk_bf16_f32 v15, v86, v87
	s_nop 1
	s_waitcnt lgkmcnt(8)
	v_mfma_f32_32x32x16_bf16 v[64:79], v[240:243], v[12:15], v[64:79]
	ds_read_b64 v[240:241], v224 offset:4448
	ds_read_b64 v[242:243], v224 offset:4464
	v_sub_f32_e32 v248, v88, v226
	v_exp_f32_e32 v88, v248
	v_sub_f32_e32 v249, v89, v226
	v_exp_f32_e32 v89, v249
	s_waitcnt lgkmcnt(8)
	v_mfma_f32_32x32x16_bf16 v[48:63], v[244:247], v[12:15], v[48:63]
	ds_read_b64 v[244:245], v224 offset:8800
	ds_read_b64 v[246:247], v224 offset:8816
	v_sub_f32_e32 v248, v90, v226
	v_exp_f32_e32 v90, v248
	v_sub_f32_e32 v249, v91, v226
	v_exp_f32_e32 v91, v249
	s_waitcnt lgkmcnt(8)
	v_mfma_f32_32x32x16_bf16 v[32:47], v[228:231], v[12:15], v[32:47]
	ds_read_b64 v[228:229], v224 offset:13152
	ds_read_b64 v[230:231], v224 offset:13168
	v_sub_f32_e32 v248, v92, v226
	v_exp_f32_e32 v92, v248
	v_sub_f32_e32 v249, v93, v226
	v_exp_f32_e32 v93, v249
	s_waitcnt lgkmcnt(8)
	v_mfma_f32_32x32x16_bf16 v[16:31], v[232:235], v[12:15], v[16:31]
	v_sub_f32_e32 v248, v94, v226
	v_exp_f32_e32 v94, v248
	v_sub_f32_e32 v249, v95, v226
	v_exp_f32_e32 v95, v249
	s_nop 0
	v_cvt_pk_bf16_f32 v8, v88, v89
	v_cvt_pk_bf16_f32 v9, v90, v91
	v_cvt_pk_bf16_f32 v10, v92, v93
	v_cvt_pk_bf16_f32 v11, v94, v95
	s_nop 1
	s_waitcnt lgkmcnt(6)
	v_mfma_f32_32x32x16_bf16 v[64:79], v[236:239], v[8:11], v[64:79]
	v_add_f32_e32 v3, v80, v96
	v_add_f32_e32 v248, v81, v97
	v_add_f32_e32 v3, v248, v3
	v_add_f32_e32 v249, v82, v98
	v_add_f32_e32 v3, v249, v3
	v_add_f32_e32 v248, v83, v99
	v_add_f32_e32 v3, v248, v3
	v_add_f32_e32 v249, v84, v100
	s_waitcnt lgkmcnt(4)
	v_mfma_f32_32x32x16_bf16 v[48:63], v[240:243], v[8:11], v[48:63]
	v_add_f32_e32 v3, v249, v3
	v_add_f32_e32 v248, v85, v101
	v_add_f32_e32 v3, v248, v3
	v_add_f32_e32 v249, v86, v102
	v_add_f32_e32 v3, v249, v3
	v_add_f32_e32 v248, v87, v103
	v_add_f32_e32 v3, v248, v3
	v_add_f32_e32 v249, v88, v104
	s_waitcnt lgkmcnt(2)
	v_mfma_f32_32x32x16_bf16 v[32:47], v[244:247], v[8:11], v[32:47]
	v_add_f32_e32 v3, v249, v3
	v_add_f32_e32 v248, v89, v105
	v_add_f32_e32 v3, v248, v3
	v_add_f32_e32 v249, v90, v106
	v_add_f32_e32 v3, v249, v3
	v_add_f32_e32 v248, v91, v107
	v_add_f32_e32 v3, v248, v3
	v_add_f32_e32 v249, v92, v108
	s_waitcnt lgkmcnt(0)
	v_mfma_f32_32x32x16_bf16 v[16:31], v[228:231], v[8:11], v[16:31]
	v_add_f32_e32 v3, v249, v3
	v_add_f32_e32 v248, v93, v109
	v_add_f32_e32 v3, v248, v3
	v_add_f32_e32 v249, v94, v110
	v_add_f32_e32 v3, v249, v3
	v_add_f32_e32 v248, v95, v111
	v_add_f32_e32 v3, v248, v3
	v_fmac_f32_e32 v3, v221, v0
	v_mov_b32_e32 v221, v3
	s_branch .LBB0_1557
